# MoBA: straight-line fast path for steps with both key tiles >=128 below the diagonal (row max on raw scores, p = exp2(fma(raw,scale2,madd-m)), hand-interleaved with PV MFMAs); f32 math unchanged in ki
# speedup vs baseline: 1.0223x; 1.0133x over previous
; #define LAS __attribute__((address_space(3)))
; #define MFMA32(a, b, c) __builtin_amdgcn_mfma_f32_32x32x16_bf16((a), (b), (c), 0, 0, 0)
; #define DMA_PAIR(u_, pb_) do { DMA16(kgu + (size_t)(2 * (u_)) * 4096 + so, (pb_)); DMA16(kgu + (size_t)(2 * (u_) + 1) * 4096 + so, (pb_) + 8192); DMA16(vgu + (size_t)(2 * (u_)) * 4096 + so, 32768 + (pb_)); DMA16(vgu + (size_t)(2 * (u_) + 1) * 4096 + so, 32768 + (pb_) + 8192); } while (0)
; template <int l> __device__ __forceinline__ void layer_body(const Args& args, LAS unsigned char* lds, const XcdBarrier& bar) {
;     ...
;                     for (int u = 0; u <= umax; ++u) {
;                         if (u < umax) DMA_PAIR(u + 1, ((u + 1) & 1) * 16384);
;                         if (2 * u <= j) {
;                             const int ta = 2 * u; const bool hasb = (ta + 1 <= j);
;                             const LAS bf16* kl = (const LAS bf16*)(lds + (u & 1) * 16384) + (hh * 32 + pr) * 8; const LAS bf16* vl = (const LAS bf16*)(lds + 32768 + (u & 1) * 16384) + (hh * 128 + r) * 8;
;                             f32x16 st0, st1;
;                             { bf16x8 kfa[8], kfb[8];
; #pragma unroll
;                               for (int s = 0; s < 8; ++s) { kfa[s] = *(const LAS bf16x8*)(kl + s * 512); kfb[s] = *(const LAS bf16x8*)(kl + 4096 + s * 512); }
; #pragma unroll
;                               for (int i = 0; i < 16; ++i) { st0[i] = 0.f; st1[i] = 0.f; }
; #pragma unroll
;                               for (int s = 0; s < 8; ++s) { st0 = MFMA32(kfa[s], qf[s], st0); st1 = MFMA32(kfb[s], qf[s], st1); } }
;                             if (hasb) logits(ta + 1, st1);
.LBB0_1512:
	s_cmp_gt_i32 s63, s61
	s_cbranch_scc1 .LBB0_1509
	s_and_b32 s76, s48, 0x4000
	v_add_u32_e32 v1, s76, v145
	ds_read_b128 v[218:221], v1
	ds_read_b128 v[222:225], v1 offset:8192
	ds_read_b128 v[226:229], v1 offset:1024
	ds_read_b128 v[230:233], v1 offset:9216
	ds_read_b128 v[234:237], v1 offset:2048
	ds_read_b128 v[238:241], v1 offset:10240
	ds_read_b128 v[242:245], v1 offset:3072
	ds_read_b128 v[246:249], v1 offset:11264
	s_lshr_b32 s77, s75, 2
	s_cmp_lt_i32 s63, s61
	s_mov_b64 s[10:11], -1
	v_add_u32_e32 v202, s76, v179
	s_waitcnt lgkmcnt(7)
	v_mfma_f32_32x32x16_bf16 v[80:95], v[218:221], v[112:115], 0
	ds_read_b128 v[218:221], v1 offset:4096
	s_waitcnt lgkmcnt(7)
	v_mfma_f32_32x32x16_bf16 v[96:111], v[222:225], v[112:115], 0
	ds_read_b128 v[222:225], v1 offset:12288
	s_waitcnt lgkmcnt(7)
	v_mfma_f32_32x32x16_bf16 v[80:95], v[226:229], v[116:119], v[80:95]
	ds_read_b128 v[226:229], v1 offset:5120
	s_waitcnt lgkmcnt(7)
	v_mfma_f32_32x32x16_bf16 v[96:111], v[230:233], v[116:119], v[96:111]
	ds_read_b128 v[230:233], v1 offset:13312
	s_waitcnt lgkmcnt(7)
	v_mfma_f32_32x32x16_bf16 v[80:95], v[234:237], v[120:123], v[80:95]
	ds_read_b128 v[234:237], v1 offset:6144
	s_waitcnt lgkmcnt(7)
	v_mfma_f32_32x32x16_bf16 v[96:111], v[238:241], v[120:123], v[96:111]
	ds_read_b128 v[238:241], v1 offset:14336
	s_waitcnt lgkmcnt(7)
	v_mfma_f32_32x32x16_bf16 v[80:95], v[242:245], v[124:127], v[80:95]
	ds_read_b128 v[242:245], v1 offset:7168
	s_waitcnt lgkmcnt(7)
	v_mfma_f32_32x32x16_bf16 v[96:111], v[246:249], v[124:127], v[96:111]
	ds_read_b128 v[246:249], v1 offset:15360
	s_waitcnt lgkmcnt(7)
	v_mfma_f32_32x32x16_bf16 v[80:95], v[218:221], v[128:131], v[80:95]
	s_waitcnt lgkmcnt(6)
	v_mfma_f32_32x32x16_bf16 v[96:111], v[222:225], v[128:131], v[96:111]
	s_waitcnt lgkmcnt(5)
	v_mfma_f32_32x32x16_bf16 v[80:95], v[226:229], v[132:135], v[80:95]
	s_waitcnt lgkmcnt(4)
	v_mfma_f32_32x32x16_bf16 v[96:111], v[230:233], v[132:135], v[96:111]
	s_waitcnt lgkmcnt(3)
	v_mfma_f32_32x32x16_bf16 v[80:95], v[234:237], v[136:139], v[80:95]
	s_waitcnt lgkmcnt(2)
	v_mfma_f32_32x32x16_bf16 v[96:111], v[238:241], v[136:139], v[96:111]
	s_waitcnt lgkmcnt(1)
	v_mfma_f32_32x32x16_bf16 v[80:95], v[242:245], v[140:143], v[80:95]
	s_waitcnt lgkmcnt(0)
	v_mfma_f32_32x32x16_bf16 v[96:111], v[246:249], v[140:143], v[96:111]
	ds_read_b128 v[218:221], v202 offset:32768
	ds_read_b128 v[222:225], v202 offset:33280
	ds_read_b128 v[226:229], v202 offset:36864
	ds_read_b128 v[230:233], v202 offset:37376
	ds_read_b128 v[234:237], v202 offset:33792
	ds_read_b128 v[238:241], v202 offset:34304
	ds_read_b128 v[242:245], v202 offset:37888
	ds_read_b128 v[246:249], v202 offset:38400
	s_xor_b32 s50, s74, 0xffffffe0
	s_add_i32 s50, s50, s66
	s_cmpk_ge_i32 s50, 0x80
	s_cbranch_scc1 .Lmoba_fast
	s_cmp_lt_i32 s63, s61
	s_cbranch_scc1 .LBB0_1515
	s_lshl_b32 s10, 1, s77
	v_and_b32_e32 v1, s10, v189
	s_mov_b64 s[10:11], 0

; template <int l> __device__ __forceinline__ void layer_body(const Args& args, LAS unsigned char* lds, const XcdBarrier& bar) {
;     ...
;                         const int n = tt >> 3; const bool sel = (n >= own) || ((selmask >> n) & 1u);
;                         if (j * 32 - (tt * 32 + 31) >= 128) { const float madd = sel ? b128 : -INFINITY; s_ = s_ * scale2 + madd; }
;     ...
;                             float tmax = fmaxf(fmaxf(st0[0], st0[1]), st0[2]);
; #pragma unroll
;                             for (int i = 3; i < 15; i += 2) tmax = fmaxf(fmaxf(tmax, st0[i]), st0[i + 1]);
;                             tmax = fmaxf(tmax, st0[15]);
; #pragma unroll
;                             for (int i = 0; i < 16; i += 2) tmax = fmaxf(fmaxf(tmax, st1[i]), st1[i + 1]);
;                             { auto rr_ = __builtin_amdgcn_permlane32_swap(__float_as_uint(tmax), __float_as_uint(tmax), false, false); tmax = fmaxf(__uint_as_float(rr_[0]), __uint_as_float(rr_[1])); }
;                             if (__any(tmax > m_run + 8.0f)) {
;                                 const float mn = fmaxf(m_run, tmax), corr = __builtin_amdgcn_exp2f(m_run - mn); m_run = mn; l_run *= corr;
; #pragma unroll
;                                 for (int dg = 0; dg < 4; ++dg) o[dg] = o[dg] * corr;
;                             }
.Lmoba_fast:
	s_lshl_b32 s10, 1, s77
	v_and_b32_e32 v1, s10, v189
	v_cmp_ne_u32_e32 vcc, 0, v1
	s_cmp_ge_i32 s77, s62
	s_cselect_b64 s[10:11], -1, 0
	s_nop 0
	s_or_b64 s[10:11], s[10:11], vcc
	s_nop 1
	v_cndmask_b32_e64 v2, v183, v188, s[10:11]
	v_max3_f32 v1, v80, v81, v82
	v_max3_f32 v3, v83, v84, v85
	v_max3_f32 v1, v1, v86, v87
	v_max3_f32 v3, v3, v88, v89
	v_max3_f32 v1, v1, v90, v91
	v_max3_f32 v3, v3, v92, v93
	v_max3_f32 v1, v1, v94, v95
	v_max3_f32 v3, v3, v96, v97
	v_max3_f32 v1, v1, v98, v99
	v_max3_f32 v3, v3, v100, v101
	v_max3_f32 v1, v1, v102, v103
	v_max3_f32 v3, v3, v104, v105
	v_max3_f32 v1, v1, v106, v107
	v_max3_f32 v3, v3, v108, v109
	v_max3_f32 v1, v1, v110, v111
	v_max_f32_e32 v1, v1, v3
	v_fma_f32 v1, v1, s46, v2
	v_mov_b32_e32 v3, v1
	s_nop 1
	v_permlane32_swap_b32_e32 v1, v3
	v_max_f32_e32 v1, v1, v3
	v_add_f32_e32 v3, 0x41000000, v193
	v_cmp_gt_f32_e32 vcc, v1, v3
	s_cbranch_vccz .Lmoba_fast_go
	v_max_f32_e32 v3, v193, v193
	v_max_f32_e32 v1, v3, v1
	v_sub_f32_e32 v4, v193, v1
	v_exp_f32_e32 v4, v4
	v_mov_b32_e32 v193, v1
	v_pk_mul_f32 v[78:79], v[78:79], v[4:5] op_sel_hi:[1,0]
	v_pk_mul_f32 v[76:77], v[76:77], v[4:5] op_sel_hi:[1,0]
	v_pk_mul_f32 v[74:75], v[74:75], v[4:5] op_sel_hi:[1,0]
	v_pk_mul_f32 v[72:73], v[72:73], v[4:5] op_sel_hi:[1,0]
	v_pk_mul_f32 v[70:71], v[70:71], v[4:5] op_sel_hi:[1,0]
	v_pk_mul_f32 v[68:69], v[68:69], v[4:5] op_sel_hi:[1,0]
	v_pk_mul_f32 v[66:67], v[66:67], v[4:5] op_sel_hi:[1,0]
	v_pk_mul_f32 v[64:65], v[64:65], v[4:5] op_sel_hi:[1,0]
	v_pk_mul_f32 v[62:63], v[62:63], v[4:5] op_sel_hi:[1,0]
	v_pk_mul_f32 v[60:61], v[60:61], v[4:5] op_sel_hi:[1,0]
	v_pk_mul_f32 v[58:59], v[58:59], v[4:5] op_sel_hi:[1,0]
	v_pk_mul_f32 v[56:57], v[56:57], v[4:5] op_sel_hi:[1,0]
	v_pk_mul_f32 v[54:55], v[54:55], v[4:5] op_sel_hi:[1,0]
	v_pk_mul_f32 v[52:53], v[52:53], v[4:5] op_sel_hi:[1,0]
	v_pk_mul_f32 v[50:51], v[50:51], v[4:5] op_sel_hi:[1,0]
	v_pk_mul_f32 v[48:49], v[48:49], v[4:5] op_sel_hi:[1,0]
	v_pk_mul_f32 v[46:47], v[46:47], v[4:5] op_sel_hi:[1,0]
	v_pk_mul_f32 v[44:45], v[44:45], v[4:5] op_sel_hi:[1,0]
	v_pk_mul_f32 v[42:43], v[42:43], v[4:5] op_sel_hi:[1,0]
	v_pk_mul_f32 v[40:41], v[40:41], v[4:5] op_sel_hi:[1,0]
	v_pk_mul_f32 v[38:39], v[38:39], v[4:5] op_sel_hi:[1,0]
	v_pk_mul_f32 v[36:37], v[36:37], v[4:5] op_sel_hi:[1,0]
	v_pk_mul_f32 v[34:35], v[34:35], v[4:5] op_sel_hi:[1,0]
	v_pk_mul_f32 v[32:33], v[32:33], v[4:5] op_sel_hi:[1,0]
	v_pk_mul_f32 v[30:31], v[30:31], v[4:5] op_sel_hi:[1,0]
	v_pk_mul_f32 v[28:29], v[28:29], v[4:5] op_sel_hi:[1,0]
	v_pk_mul_f32 v[26:27], v[26:27], v[4:5] op_sel_hi:[1,0]
	v_pk_mul_f32 v[24:25], v[24:25], v[4:5] op_sel_hi:[1,0]
	v_pk_mul_f32 v[22:23], v[22:23], v[4:5] op_sel_hi:[1,0]
	v_pk_mul_f32 v[20:21], v[20:21], v[4:5] op_sel_hi:[1,0]
	v_pk_mul_f32 v[18:19], v[18:19], v[4:5] op_sel_hi:[1,0]
	v_pk_mul_f32 v[16:17], v[16:17], v[4:5] op_sel_hi:[1,0]
	v_mul_f32_e32 v190, v190, v4
; template <int l> __device__ __forceinline__ void layer_body(const Args& args, LAS unsigned char* lds, const XcdBarrier& bar) {
;     ...
;                             st0 = st0 - m_run; st1 = st1 - m_run;
; #pragma unroll
;                             for (int i = 0; i < 16; ++i) { st0[i] = __builtin_amdgcn_exp2f(st0[i]); st1[i] = __builtin_amdgcn_exp2f(st1[i]); }
;                             { float ps = (((st0[0] + st0[1]) + (st0[2] + st0[3])) + ((st0[4] + st0[5]) + (st0[6] + st0[7]))) + (((st0[8] + st0[9]) + (st0[10] + st0[11])) + ((st0[12] + st0[13]) + (st0[14] + st0[15])));
;                               ps += (((st1[0] + st1[1]) + (st1[2] + st1[3])) + ((st1[4] + st1[5]) + (st1[6] + st1[7]))) + (((st1[8] + st1[9]) + (st1[10] + st1[11])) + ((st1[12] + st1[13]) + (st1[14] + st1[15])));
;                               { auto rr_ = __builtin_amdgcn_permlane32_swap(__float_as_uint(ps), __float_as_uint(ps), false, false); ps = __uint_as_float(rr_[0]) + __uint_as_float(rr_[1]); }
;                               l_run += ps; }
;                             { v4u p0, p1; p0.x = cvtpk(st0[0], st0[1]); p0.y = cvtpk(st0[2], st0[3]); p0.z = cvtpk(st0[4], st0[5]); p0.w = cvtpk(st0[6], st0[7]);
;                               p1.x = cvtpk(st0[8], st0[9]); p1.y = cvtpk(st0[10], st0[11]); p1.z = cvtpk(st0[12], st0[13]); p1.w = cvtpk(st0[14], st0[15]);
;                               const bf16x8 pf0 = __builtin_bit_cast(bf16x8, p0), pf1 = __builtin_bit_cast(bf16x8, p1);
; #pragma unroll
;                               for (int dg = 0; dg < 4; ++dg) { o[dg] = MFMA32(*(const LAS bf16x8*)(vl + dg * 256), pf0, o[dg]); o[dg] = MFMA32(*(const LAS bf16x8*)(vl + 2048 + dg * 256), pf1, o[dg]); } }
;                             { v4u p0, p1; p0.x = cvtpk(st1[0], st1[1]); p0.y = cvtpk(st1[2], st1[3]); p0.z = cvtpk(st1[4], st1[5]); p0.w = cvtpk(st1[6], st1[7]);
;                               p1.x = cvtpk(st1[8], st1[9]); p1.y = cvtpk(st1[10], st1[11]); p1.z = cvtpk(st1[12], st1[13]); p1.w = cvtpk(st1[14], st1[15]);
;                               const bf16x8 pf0 = __builtin_bit_cast(bf16x8, p0), pf1 = __builtin_bit_cast(bf16x8, p1);
; #pragma unroll
;                               for (int dg = 0; dg < 4; ++dg) { o[dg] = MFMA32(*(const LAS bf16x8*)(vl + 4096 + dg * 256), pf0, o[dg]); o[dg] = MFMA32(*(const LAS bf16x8*)(vl + 4096 + 2048 + dg * 256), pf1, o[dg]); } }
.Lmoba_fast_go:
	v_sub_f32_e32 v3, v2, v193
	v_fma_f32 v80, v80, s46, v3
	v_fma_f32 v81, v81, s46, v3
	v_fma_f32 v82, v82, s46, v3
	v_fma_f32 v83, v83, s46, v3
	v_fma_f32 v84, v84, s46, v3
	v_fma_f32 v85, v85, s46, v3
	v_fma_f32 v86, v86, s46, v3
	v_fma_f32 v87, v87, s46, v3
	v_exp_f32_e32 v80, v80
	v_exp_f32_e32 v81, v81
	v_exp_f32_e32 v82, v82
	v_exp_f32_e32 v83, v83
	v_exp_f32_e32 v84, v84
	v_exp_f32_e32 v85, v85
	v_exp_f32_e32 v86, v86
	v_exp_f32_e32 v87, v87
	v_cvt_pk_bf16_f32 v4, v80, v81
	v_cvt_pk_bf16_f32 v5, v82, v83
	v_cvt_pk_bf16_f32 v6, v84, v85
	v_cvt_pk_bf16_f32 v7, v86, v87
	s_nop 0
	s_waitcnt lgkmcnt(7)
	v_mfma_f32_32x32x16_bf16 v[64:79], v[218:221], v[4:7], v[64:79]
	ds_read_b128 v[218:221], v202 offset:40960
	s_waitcnt lgkmcnt(7)
	v_mfma_f32_32x32x16_bf16 v[48:63], v[222:225], v[4:7], v[48:63]
	ds_read_b128 v[222:225], v202 offset:41472
	v_fma_f32 v88, v88, s46, v3
	v_fma_f32 v89, v89, s46, v3
	v_fma_f32 v90, v90, s46, v3
	v_fma_f32 v91, v91, s46, v3
	v_fma_f32 v92, v92, s46, v3
	v_fma_f32 v93, v93, s46, v3
	v_fma_f32 v94, v94, s46, v3
	v_fma_f32 v95, v95, s46, v3
	v_exp_f32_e32 v88, v88
	v_exp_f32_e32 v89, v89
	v_exp_f32_e32 v90, v90
	v_exp_f32_e32 v91, v91
	v_exp_f32_e32 v92, v92
	v_exp_f32_e32 v93, v93
	v_exp_f32_e32 v94, v94
	v_exp_f32_e32 v95, v95
	v_cvt_pk_bf16_f32 v8, v88, v89
	v_cvt_pk_bf16_f32 v9, v90, v91
	v_cvt_pk_bf16_f32 v10, v92, v93
	v_cvt_pk_bf16_f32 v11, v94, v95
	s_nop 0
	s_waitcnt lgkmcnt(7)
	v_mfma_f32_32x32x16_bf16 v[64:79], v[226:229], v[8:11], v[64:79]
	ds_read_b128 v[226:229], v202 offset:45056
	s_waitcnt lgkmcnt(7)
	v_mfma_f32_32x32x16_bf16 v[48:63], v[230:233], v[8:11], v[48:63]
	ds_read_b128 v[230:233], v202 offset:45568
	s_waitcnt lgkmcnt(7)
	v_mfma_f32_32x32x16_bf16 v[32:47], v[234:237], v[4:7], v[32:47]
	ds_read_b128 v[234:237], v202 offset:41984
	s_waitcnt lgkmcnt(7)
	v_mfma_f32_32x32x16_bf16 v[16:31], v[238:241], v[4:7], v[16:31]
	ds_read_b128 v[238:241], v202 offset:42496
	v_fma_f32 v96, v96, s46, v3
	v_fma_f32 v97, v97, s46, v3
	v_fma_f32 v98, v98, s46, v3
	v_fma_f32 v99, v99, s46, v3
	v_fma_f32 v100, v100, s46, v3
	v_fma_f32 v101, v101, s46, v3
	v_fma_f32 v102, v102, s46, v3
	v_fma_f32 v103, v103, s46, v3
	v_exp_f32_e32 v96, v96
	v_exp_f32_e32 v97, v97
	v_exp_f32_e32 v98, v98
	v_exp_f32_e32 v99, v99
	v_exp_f32_e32 v100, v100
	v_exp_f32_e32 v101, v101
	v_exp_f32_e32 v102, v102
	v_exp_f32_e32 v103, v103
	v_cvt_pk_bf16_f32 v12, v96, v97
	v_cvt_pk_bf16_f32 v13, v98, v99
	v_cvt_pk_bf16_f32 v14, v100, v101
	v_cvt_pk_bf16_f32 v15, v102, v103
	s_waitcnt lgkmcnt(7)
	v_mfma_f32_32x32x16_bf16 v[32:47], v[242:245], v[8:11], v[32:47]
	ds_read_b128 v[242:245], v202 offset:46080
	s_waitcnt lgkmcnt(7)
	v_mfma_f32_32x32x16_bf16 v[16:31], v[246:249], v[8:11], v[16:31]
	ds_read_b128 v[246:249], v202 offset:46592
	v_fma_f32 v104, v104, s46, v3
	v_fma_f32 v105, v105, s46, v3
	v_fma_f32 v106, v106, s46, v3
	v_fma_f32 v107, v107, s46, v3
	v_fma_f32 v108, v108, s46, v3
	v_fma_f32 v109, v109, s46, v3
	v_fma_f32 v110, v110, s46, v3
	v_fma_f32 v111, v111, s46, v3
	v_exp_f32_e32 v104, v104
	v_exp_f32_e32 v105, v105
	v_exp_f32_e32 v106, v106
	v_exp_f32_e32 v107, v107
	v_exp_f32_e32 v108, v108
	v_exp_f32_e32 v109, v109
	v_exp_f32_e32 v110, v110
	v_exp_f32_e32 v111, v111
	v_cvt_pk_bf16_f32 v194, v104, v105
	v_cvt_pk_bf16_f32 v195, v106, v107
	v_cvt_pk_bf16_f32 v196, v108, v109
	v_cvt_pk_bf16_f32 v197, v110, v111
	s_nop 0
	s_waitcnt lgkmcnt(7)
	v_mfma_f32_32x32x16_bf16 v[64:79], v[218:221], v[12:15], v[64:79]
	s_waitcnt lgkmcnt(6)
	v_mfma_f32_32x32x16_bf16 v[48:63], v[222:225], v[12:15], v[48:63]
	v_add_f32_e32 v198, v80, v81
	v_add_f32_e32 v199, v82, v83
	v_add_f32_e32 v198, v198, v84
	v_add_f32_e32 v199, v199, v85
	v_add_f32_e32 v198, v198, v86
	v_add_f32_e32 v199, v199, v87
	v_add_f32_e32 v198, v198, v199
	s_waitcnt lgkmcnt(5)
	v_mfma_f32_32x32x16_bf16 v[64:79], v[226:229], v[194:197], v[64:79]
	s_waitcnt lgkmcnt(4)
	v_mfma_f32_32x32x16_bf16 v[48:63], v[230:233], v[194:197], v[48:63]
	v_add_f32_e32 v200, v88, v89
	v_add_f32_e32 v201, v90, v91
	v_add_f32_e32 v200, v200, v92
	v_add_f32_e32 v201, v201, v93
	v_add_f32_e32 v200, v200, v94
	v_add_f32_e32 v201, v201, v95
	v_add_f32_e32 v200, v200, v201
	s_waitcnt lgkmcnt(3)
	v_mfma_f32_32x32x16_bf16 v[32:47], v[234:237], v[12:15], v[32:47]
	s_waitcnt lgkmcnt(2)
	v_mfma_f32_32x32x16_bf16 v[16:31], v[238:241], v[12:15], v[16:31]
	v_add_f32_e32 v206, v96, v97
	v_add_f32_e32 v207, v98, v99
	v_add_f32_e32 v206, v206, v100
	v_add_f32_e32 v207, v207, v101
	v_add_f32_e32 v206, v206, v102
	v_add_f32_e32 v207, v207, v103
	v_add_f32_e32 v206, v206, v207
	s_waitcnt lgkmcnt(1)
	v_mfma_f32_32x32x16_bf16 v[32:47], v[242:245], v[194:197], v[32:47]
	v_add_f32_e32 v208, v104, v105
	v_add_f32_e32 v209, v106, v107
	v_add_f32_e32 v208, v208, v108
	v_add_f32_e32 v209, v209, v109
	v_add_f32_e32 v208, v208, v110
	v_add_f32_e32 v209, v209, v111
	v_add_f32_e32 v208, v208, v209
	s_waitcnt lgkmcnt(0)
	v_mfma_f32_32x32x16_bf16 v[16:31], v[246:249], v[194:197], v[16:31]
	v_add_f32_e32 v198, v198, v200
	v_add_f32_e32 v206, v206, v208
	v_add_f32_e32 v198, v198, v206
	v_mov_b32_e32 v1, v198
	s_nop 1
	v_permlane32_swap_b32_e32 v198, v1
	v_add_f32_e32 v1, v198, v1
	v_add_f32_e32 v190, v190, v1
	s_branch .LBB0_1509
